# phase 0: silu(cond) staging issues its six loads together (was a six-iteration load-wait loop at kernel start)
# speedup vs baseline: 1.0210x; 1.0003x over previous
.LBB0_19:
	v_add_u32_e32 v18, 0, v18
	s_ashr_i32 s20, s24, 31
	v_add_u32_e32 v22, 0x400, v18
	s_mov_b64 s[4:5], 0
	s_movk_i32 s21, 0x3ff
	s_mov_b32 s29, 0x7ffffc00
	v_mov_b32_e32 v19, 0
	s_movk_i32 s34, 0x9ff
	v_mov_b32_e32 v23, v0
	ds_read_b64 v[200:201], v19 offset:136
	ds_read_b64 v[202:203], v19 offset:128
	v_add_u32_e32 v204, 0x1000, v18
	s_waitcnt lgkmcnt(0)
	v_readfirstlane_b32 s10, v200
	v_readfirstlane_b32 s11, v201
	v_readfirstlane_b32 s12, v202
	v_readfirstlane_b32 s13, v203
	s_nop 4
	global_load_dword v205, v18, s[10:11]
	global_load_dword v206, v18, s[10:11] offset:2048
	global_load_dword v207, v18, s[12:13]
	global_load_dword v208, v18, s[12:13] offset:2048
	global_load_dword v209, v204, s[12:13]
	global_load_dword v210, v204, s[12:13] offset:2048
	s_waitcnt vmcnt(0)
	v_mul_f32_e32 v211, 0xbfb8aa3b, v205
	v_mul_f32_e32 v212, 0xbfb8aa3b, v206
	v_mul_f32_e32 v213, 0xbfb8aa3b, v207
	v_mul_f32_e32 v214, 0xbfb8aa3b, v208
	v_mul_f32_e32 v215, 0xbfb8aa3b, v209
	v_mul_f32_e32 v216, 0xbfb8aa3b, v210
	v_exp_f32_e32 v211, v211
	v_exp_f32_e32 v212, v212
	v_exp_f32_e32 v213, v213
	v_exp_f32_e32 v214, v214
	v_exp_f32_e32 v215, v215
	v_exp_f32_e32 v216, v216
	v_add_f32_e32 v211, 1.0, v211
	v_add_f32_e32 v212, 1.0, v212
	v_add_f32_e32 v213, 1.0, v213
	v_add_f32_e32 v214, 1.0, v214
	v_add_f32_e32 v215, 1.0, v215
	v_add_f32_e32 v216, 1.0, v216
	v_rcp_f32_e32 v211, v211
	v_rcp_f32_e32 v212, v212
	v_rcp_f32_e32 v213, v213
	v_rcp_f32_e32 v214, v214
	v_rcp_f32_e32 v215, v215
	v_rcp_f32_e32 v216, v216
	v_mul_f32_e32 v205, v205, v211
	v_mul_f32_e32 v206, v206, v212
	v_mul_f32_e32 v207, v207, v213
	v_mul_f32_e32 v208, v208, v214
	v_mul_f32_e32 v209, v209, v215
	v_mul_f32_e32 v210, v210, v216
	ds_write_b32 v22, v205
	ds_write_b32 v22, v206 offset:2048
	ds_write_b32 v22, v207 offset:4096
	ds_write_b32 v22, v208 offset:6144
	ds_write_b32 v22, v209 offset:8192
	ds_write_b32 v22, v210 offset:10240
